# v32: attention: stream 0 fetches stream 1's tiles 0-2 in its last three loop iterations and its Q fragments before the drain; stream 1 starts without a load prologue
# baseline (speedup 1.0000x reference)
.Lat_stream:
	s_mov_b32 s9, 0
	v_lshl_add_u64 v[182:183], v[166:167], 0, 0
	global_load_dwordx4 v[150:153], v[182:183], off
	global_load_dwordx4 v[146:149], v[182:183], off offset:32
	global_load_dwordx4 v[142:145], v[182:183], off offset:64
	global_load_dwordx4 v[138:141], v[182:183], off offset:96
	s_lshl_b64 s[14:15], s[46:47], 12
	s_add_u32 s14, s14, s74
	s_addc_u32 s15, s15, s75
	s_add_u32 s18, s14, 0x800
	s_addc_u32 s19, s15, 0
	s_add_u32 s14, s14, 0x400
	s_addc_u32 s15, s15, 0
	s_mov_b32 s13, 0
	s_mov_b32 s17, 32768
	s_mov_b32 s85, 0
	s_add_i32 s10, s6, -1
	s_lshl_b32 s10, s10, 18
	s_sub_u32 s10, 0, s10
	s_mov_b32 s11, -1
	s_add_i32 m0, s13, s68
	s_nop 0
	global_load_lds_dwordx4 v154, s[14:15]
	s_add_i32 m0, s17, s69
	s_nop 0
	global_load_lds_dwordx4 v155, s[18:19]
	s_add_i32 m0, m0, 0x400
	s_nop 0
	global_load_lds_dwordx4 v156, s[18:19]
	s_add_i32 s13, s13, 8192
	s_cmp_eq_u32 s13, 32768
	s_cselect_b32 s13, 0, s13
	s_add_i32 s17, s17, 16384
	s_cmp_eq_u32 s17, 114688
	s_cselect_b32 s17, 32768, s17
	s_add_i32 s85, s85, 1
	s_cmp_eq_u32 s85, s6
	s_cselect_b32 s8, s10, 0x40000
	s_cselect_b32 s16, s11, 0
	s_cselect_b32 s9, 0x80, 0
	s_add_u32 s18, s18, s8
	s_addc_u32 s19, s19, s16
	s_add_u32 s14, s14, s8
	s_addc_u32 s15, s15, s16
	s_add_u32 s14, s14, s9
	s_addc_u32 s15, s15, 0
	s_add_i32 m0, s13, s68
	s_nop 0
	global_load_lds_dwordx4 v154, s[14:15]
	s_add_i32 m0, s17, s69
	s_nop 0
	global_load_lds_dwordx4 v155, s[18:19]
	s_add_i32 m0, m0, 0x400
	s_nop 0
	global_load_lds_dwordx4 v156, s[18:19]
	s_add_i32 s13, s13, 8192
	s_cmp_eq_u32 s13, 32768
	s_cselect_b32 s13, 0, s13
	s_add_i32 s17, s17, 16384
	s_cmp_eq_u32 s17, 114688
	s_cselect_b32 s17, 32768, s17
	s_add_i32 s85, s85, 1
	s_cmp_eq_u32 s85, s6
	s_cselect_b32 s8, s10, 0x40000
	s_cselect_b32 s16, s11, 0
	s_cselect_b32 s9, 0x80, 0
	s_add_u32 s18, s18, s8
	s_addc_u32 s19, s19, s16
	s_add_u32 s14, s14, s8
	s_addc_u32 s15, s15, s16
	s_add_u32 s14, s14, s9
	s_addc_u32 s15, s15, 0
	s_add_i32 m0, s13, s68
	s_nop 0
	global_load_lds_dwordx4 v154, s[14:15]
	s_add_i32 m0, s17, s69
	s_nop 0
	global_load_lds_dwordx4 v155, s[18:19]
	s_add_i32 m0, m0, 0x400
	s_nop 0
	global_load_lds_dwordx4 v156, s[18:19]
	s_add_i32 s13, s13, 8192
	s_cmp_eq_u32 s13, 32768
	s_cselect_b32 s13, 0, s13
	s_add_i32 s17, s17, 16384
	s_cmp_eq_u32 s17, 114688
	s_cselect_b32 s17, 32768, s17
	s_add_i32 s85, s85, 1
	s_cmp_eq_u32 s85, s6
	s_cselect_b32 s8, s10, 0x40000
	s_cselect_b32 s16, s11, 0
	s_cselect_b32 s9, 0x80, 0
	s_add_u32 s18, s18, s8
	s_addc_u32 s19, s19, s16
	s_add_u32 s14, s14, s8
	s_addc_u32 s15, s15, s16
	s_add_u32 s14, s14, s9
	s_addc_u32 s15, s15, 0
	v_mov_b32_e32 v0, 0
	v_mov_b32_e32 v1, v0
	v_mov_b32_e32 v2, v0
	v_mov_b32_e32 v3, v0
	v_mov_b32_e32 v4, v0
	v_mov_b32_e32 v5, v0
	v_mov_b32_e32 v6, v0
	v_mov_b32_e32 v7, v0
	v_mov_b32_e32 v8, v0
	v_mov_b32_e32 v9, v0
	v_mov_b32_e32 v10, v0
	v_mov_b32_e32 v11, v0
	v_mov_b32_e32 v12, v0
	v_mov_b32_e32 v13, v0
	v_mov_b32_e32 v14, v0
	v_mov_b32_e32 v15, v0
	v_mov_b32_e32 v16, v0
	v_mov_b32_e32 v17, v0
	v_mov_b32_e32 v18, v0
	v_mov_b32_e32 v19, v0
	v_mov_b32_e32 v20, v0
	v_mov_b32_e32 v21, v0
	v_mov_b32_e32 v22, v0
	v_mov_b32_e32 v23, v0
	v_mov_b32_e32 v24, v0
	v_mov_b32_e32 v25, v0
	v_mov_b32_e32 v26, v0
	v_mov_b32_e32 v27, v0
	v_mov_b32_e32 v28, v0
	v_mov_b32_e32 v29, v0
	v_mov_b32_e32 v30, v0
	v_mov_b32_e32 v31, v0
	v_mov_b32_e32 v32, v0
	v_mov_b32_e32 v33, v0
	v_mov_b32_e32 v34, v0
	v_mov_b32_e32 v35, v0
	v_mov_b32_e32 v36, v0
	v_mov_b32_e32 v37, v0
	v_mov_b32_e32 v38, v0
	v_mov_b32_e32 v39, v0
	v_mov_b32_e32 v40, v0
	v_mov_b32_e32 v41, v0
	v_mov_b32_e32 v42, v0
	v_mov_b32_e32 v43, v0
	v_mov_b32_e32 v44, v0
	v_mov_b32_e32 v45, v0
	v_mov_b32_e32 v46, v0
	v_mov_b32_e32 v47, v0
	v_mov_b32_e32 v48, v0
	v_mov_b32_e32 v49, v0
	v_mov_b32_e32 v50, v0
	v_mov_b32_e32 v51, v0
	v_mov_b32_e32 v52, v0
	v_mov_b32_e32 v53, v0
	v_mov_b32_e32 v54, v0
	v_mov_b32_e32 v55, v0
	v_mov_b32_e32 v56, v0
	v_mov_b32_e32 v57, v0
	v_mov_b32_e32 v58, v0
	v_mov_b32_e32 v59, v0
	v_mov_b32_e32 v60, v0
	v_mov_b32_e32 v61, v0
	v_mov_b32_e32 v62, v0
	v_mov_b32_e32 v63, v0
	v_mov_b32_e32 v64, v0
	v_mov_b32_e32 v65, v0
	v_mov_b32_e32 v66, v0
	v_mov_b32_e32 v67, v0
	v_mov_b32_e32 v68, v0
	v_mov_b32_e32 v69, v0
	v_mov_b32_e32 v70, v0
	v_mov_b32_e32 v71, v0
	v_mov_b32_e32 v72, v0
	v_mov_b32_e32 v73, v0
	v_mov_b32_e32 v74, v0
	v_mov_b32_e32 v75, v0
	v_mov_b32_e32 v76, v0
	v_mov_b32_e32 v77, v0
	v_mov_b32_e32 v78, v0
	v_mov_b32_e32 v79, v0
	v_mov_b32_e32 v80, 0
	v_mov_b32_e32 v81, 0
	s_waitcnt vmcnt(3)
	s_branch .Lat_stream_go
.Lat_stream1:
	s_mov_b32 s85, 3
	s_mov_b32 s10, 0x40000
	s_mov_b32 s11, 0
	v_mov_b32_e32 v0, 0
	v_mov_b32_e32 v1, v0
	v_mov_b32_e32 v2, v0
	v_mov_b32_e32 v3, v0
	v_mov_b32_e32 v4, v0
	v_mov_b32_e32 v5, v0
	v_mov_b32_e32 v6, v0
	v_mov_b32_e32 v7, v0
	v_mov_b32_e32 v8, v0
	v_mov_b32_e32 v9, v0
	v_mov_b32_e32 v10, v0
	v_mov_b32_e32 v11, v0
	v_mov_b32_e32 v12, v0
	v_mov_b32_e32 v13, v0
	v_mov_b32_e32 v14, v0
	v_mov_b32_e32 v15, v0
	v_mov_b32_e32 v16, v0
	v_mov_b32_e32 v17, v0
	v_mov_b32_e32 v18, v0
	v_mov_b32_e32 v19, v0
	v_mov_b32_e32 v20, v0
	v_mov_b32_e32 v21, v0
	v_mov_b32_e32 v22, v0
	v_mov_b32_e32 v23, v0
	v_mov_b32_e32 v24, v0
	v_mov_b32_e32 v25, v0
	v_mov_b32_e32 v26, v0
	v_mov_b32_e32 v27, v0
	v_mov_b32_e32 v28, v0
	v_mov_b32_e32 v29, v0
	v_mov_b32_e32 v30, v0
	v_mov_b32_e32 v31, v0
	v_mov_b32_e32 v32, v0
	v_mov_b32_e32 v33, v0
	v_mov_b32_e32 v34, v0
	v_mov_b32_e32 v35, v0
	v_mov_b32_e32 v36, v0
	v_mov_b32_e32 v37, v0
	v_mov_b32_e32 v38, v0
	v_mov_b32_e32 v39, v0
	v_mov_b32_e32 v40, v0
	v_mov_b32_e32 v41, v0
	v_mov_b32_e32 v42, v0
	v_mov_b32_e32 v43, v0
	v_mov_b32_e32 v44, v0
	v_mov_b32_e32 v45, v0
	v_mov_b32_e32 v46, v0
	v_mov_b32_e32 v47, v0
	v_mov_b32_e32 v48, v0
	v_mov_b32_e32 v49, v0
	v_mov_b32_e32 v50, v0
	v_mov_b32_e32 v51, v0
	v_mov_b32_e32 v52, v0
	v_mov_b32_e32 v53, v0
	v_mov_b32_e32 v54, v0
	v_mov_b32_e32 v55, v0
	v_mov_b32_e32 v56, v0
	v_mov_b32_e32 v57, v0
	v_mov_b32_e32 v58, v0
	v_mov_b32_e32 v59, v0
	v_mov_b32_e32 v60, v0
	v_mov_b32_e32 v61, v0
	v_mov_b32_e32 v62, v0
	v_mov_b32_e32 v63, v0
	v_mov_b32_e32 v64, v0
	v_mov_b32_e32 v65, v0
	v_mov_b32_e32 v66, v0
	v_mov_b32_e32 v67, v0
	v_mov_b32_e32 v68, v0
	v_mov_b32_e32 v69, v0
	v_mov_b32_e32 v70, v0
	v_mov_b32_e32 v71, v0
	v_mov_b32_e32 v72, v0
	v_mov_b32_e32 v73, v0
	v_mov_b32_e32 v74, v0
	v_mov_b32_e32 v75, v0
	v_mov_b32_e32 v76, v0
	v_mov_b32_e32 v77, v0
	v_mov_b32_e32 v78, v0
	v_mov_b32_e32 v79, v0
	v_mov_b32_e32 v80, 0
	v_mov_b32_e32 v81, 0
	s_waitcnt vmcnt(16)
.Lat_stream_go:
	s_mov_b32 s5, 0
	s_barrier
	s_add_i32 s12, s13, 8192
	s_cmp_ge_u32 s12, 32768
	s_cselect_b32 s8, 32768, 0
	s_sub_i32 s12, s12, s8
	s_add_i32 s84, s17, 32768
	s_cmp_ge_u32 s84, 114688
	s_cselect_b32 s8, 81920, 0
	s_sub_i32 s84, s84, s8
	s_add_i32 m0, s13, s68
	s_nop 0
	global_load_lds_dwordx4 v154, s[14:15]
	s_add_i32 m0, s17, s69
	s_nop 0
	global_load_lds_dwordx4 v155, s[18:19]
	s_add_i32 m0, m0, 0x400
	s_nop 0
	global_load_lds_dwordx4 v156, s[18:19]
	s_add_i32 s13, s13, 8192
	s_cmp_eq_u32 s13, 32768
	s_cselect_b32 s13, 0, s13
	s_add_i32 s17, s17, 16384
	s_cmp_eq_u32 s17, 114688
	s_cselect_b32 s17, 32768, s17
	s_add_i32 s85, s85, 1
	s_cmp_eq_u32 s85, s6
	s_cselect_b32 s8, s10, 0x40000
	s_cselect_b32 s16, s11, 0
	s_cselect_b32 s9, 0x80, 0
	s_add_u32 s18, s18, s8
	s_addc_u32 s19, s19, s16
	s_add_u32 s14, s14, s8
	s_addc_u32 s15, s15, s16
	s_add_u32 s14, s14, s9
	s_addc_u32 s15, s15, 0
	v_add_u32_e32 v188, s12, v157
	v_add_u32_e32 v189, s12, v158
	v_add_u32_e32 v222, s12, v159
	v_add_u32_e32 v223, s12, v160
	ds_read_b128 v[224:227], v188
	ds_read_b128 v[228:231], v189
	ds_read_b128 v[232:235], v222
	ds_read_b128 v[236:239], v223
	ds_read_b128 v[240:243], v188 offset:4096
	ds_read_b128 v[130:133], v189 offset:4096
	ds_read_b128 v[134:137], v222 offset:4096
	ds_read_b128 v[184:187], v223 offset:4096
	s_waitcnt lgkmcnt(7)
	v_mfma_f32_32x32x16_bf16 v[82:97], v[224:227], v[150:153], v[64:79]
	s_waitcnt lgkmcnt(6)
	v_mfma_f32_32x32x16_bf16 v[82:97], v[228:231], v[146:149], v[82:97]
	s_waitcnt lgkmcnt(5)
	v_mfma_f32_32x32x16_bf16 v[82:97], v[232:235], v[142:145], v[82:97]
	s_waitcnt lgkmcnt(4)
	v_mfma_f32_32x32x16_bf16 v[82:97], v[236:239], v[138:141], v[82:97]
	s_waitcnt lgkmcnt(3)
	v_mfma_f32_32x32x16_bf16 v[98:113], v[240:243], v[150:153], v[64:79]
	s_waitcnt lgkmcnt(2)
	v_mfma_f32_32x32x16_bf16 v[98:113], v[130:133], v[146:149], v[98:113]
	s_waitcnt lgkmcnt(1)
	v_mfma_f32_32x32x16_bf16 v[98:113], v[134:137], v[142:145], v[98:113]
	s_waitcnt lgkmcnt(0)
	v_mfma_f32_32x32x16_bf16 v[98:113], v[184:187], v[138:141], v[98:113]
	s_nop 11
	v_max_f32_e32 v181, v82, v98
	v_max3_f32 v181, v181, v83, v99
	v_max3_f32 v181, v181, v84, v100
	v_max3_f32 v181, v181, v85, v101
	v_max3_f32 v181, v181, v86, v102
	v_max3_f32 v181, v181, v87, v103
	v_max3_f32 v181, v181, v88, v104
	v_max3_f32 v181, v181, v89, v105
	v_max3_f32 v181, v181, v90, v106
	v_max3_f32 v181, v181, v91, v107
	v_max3_f32 v181, v181, v92, v108
	v_max3_f32 v181, v181, v93, v109
	v_max3_f32 v181, v181, v94, v110
	v_max3_f32 v181, v181, v95, v111
	v_max3_f32 v181, v181, v96, v112
	v_max3_f32 v181, v181, v97, v113
	ds_bpermute_b32 v182, v214, v181
	s_waitcnt lgkmcnt(0)
	v_max_f32_e32 v80, v181, v182
	v_xor_b32_e32 v64, 0x80000000, v80
	v_mov_b32_e32 v65, v64
	v_mov_b32_e32 v66, v64
	v_mov_b32_e32 v67, v64
	v_mov_b32_e32 v68, v64
	v_mov_b32_e32 v69, v64
	v_mov_b32_e32 v70, v64
	v_mov_b32_e32 v71, v64
	v_mov_b32_e32 v72, v64
	v_mov_b32_e32 v73, v64
	v_mov_b32_e32 v74, v64
	v_mov_b32_e32 v75, v64
	v_mov_b32_e32 v76, v64
	v_mov_b32_e32 v77, v64
	v_mov_b32_e32 v78, v64
	v_mov_b32_e32 v79, v64
	v_sub_f32_e32 v82, v82, v80
	v_sub_f32_e32 v83, v83, v80
	v_sub_f32_e32 v84, v84, v80
	v_sub_f32_e32 v85, v85, v80
	v_sub_f32_e32 v86, v86, v80
	v_sub_f32_e32 v87, v87, v80
	v_sub_f32_e32 v88, v88, v80
	v_sub_f32_e32 v89, v89, v80
	v_sub_f32_e32 v90, v90, v80
	v_sub_f32_e32 v91, v91, v80
	v_sub_f32_e32 v92, v92, v80
	v_sub_f32_e32 v93, v93, v80
	v_sub_f32_e32 v94, v94, v80
	v_sub_f32_e32 v95, v95, v80
	v_sub_f32_e32 v96, v96, v80
	v_sub_f32_e32 v97, v97, v80
	v_sub_f32_e32 v98, v98, v80
	v_sub_f32_e32 v99, v99, v80
	v_sub_f32_e32 v100, v100, v80
	v_sub_f32_e32 v101, v101, v80
	v_sub_f32_e32 v102, v102, v80
	v_sub_f32_e32 v103, v103, v80
	v_sub_f32_e32 v104, v104, v80
	v_sub_f32_e32 v105, v105, v80
	v_sub_f32_e32 v106, v106, v80
	v_sub_f32_e32 v107, v107, v80
	v_sub_f32_e32 v108, v108, v80
	v_sub_f32_e32 v109, v109, v80
	v_sub_f32_e32 v110, v110, v80
	v_sub_f32_e32 v111, v111, v80
	v_sub_f32_e32 v112, v112, v80
	v_sub_f32_e32 v113, v113, v80
	v_mov_b32_e32 v180, 0
	v_exp_f32_e32 v82, v82
	v_exp_f32_e32 v83, v83
	v_add_f32_e32 v180, v180, v82
	v_exp_f32_e32 v84, v84
	v_add_f32_e32 v180, v180, v83
	v_exp_f32_e32 v85, v85
	v_add_f32_e32 v180, v180, v84
	v_exp_f32_e32 v86, v86
	v_add_f32_e32 v180, v180, v85
	v_exp_f32_e32 v87, v87
	v_add_f32_e32 v180, v180, v86
	v_exp_f32_e32 v88, v88
	v_add_f32_e32 v180, v180, v87
	v_exp_f32_e32 v89, v89
	v_add_f32_e32 v180, v180, v88
	v_exp_f32_e32 v90, v90
	v_add_f32_e32 v180, v180, v89
	v_exp_f32_e32 v91, v91
	v_add_f32_e32 v180, v180, v90
	v_exp_f32_e32 v92, v92
	v_add_f32_e32 v180, v180, v91
	v_exp_f32_e32 v93, v93
	v_add_f32_e32 v180, v180, v92
	v_exp_f32_e32 v94, v94
	v_add_f32_e32 v180, v180, v93
	v_exp_f32_e32 v95, v95
	v_add_f32_e32 v180, v180, v94
	v_exp_f32_e32 v96, v96
	v_add_f32_e32 v180, v180, v95
	v_exp_f32_e32 v97, v97
	v_add_f32_e32 v180, v180, v96
	v_exp_f32_e32 v98, v98
	v_add_f32_e32 v180, v180, v97
	v_exp_f32_e32 v99, v99
	v_add_f32_e32 v180, v180, v98
	v_exp_f32_e32 v100, v100
	v_add_f32_e32 v180, v180, v99
	v_exp_f32_e32 v101, v101
	v_add_f32_e32 v180, v180, v100
	v_exp_f32_e32 v102, v102
	v_add_f32_e32 v180, v180, v101
	v_exp_f32_e32 v103, v103
	v_add_f32_e32 v180, v180, v102
	v_exp_f32_e32 v104, v104
	v_add_f32_e32 v180, v180, v103
	v_exp_f32_e32 v105, v105
	v_add_f32_e32 v180, v180, v104
	v_exp_f32_e32 v106, v106
	v_add_f32_e32 v180, v180, v105
	v_exp_f32_e32 v107, v107
	v_add_f32_e32 v180, v180, v106
	v_exp_f32_e32 v108, v108
	v_add_f32_e32 v180, v180, v107
	v_exp_f32_e32 v109, v109
	v_add_f32_e32 v180, v180, v108
	v_exp_f32_e32 v110, v110
	v_add_f32_e32 v180, v180, v109
	v_exp_f32_e32 v111, v111
	v_add_f32_e32 v180, v180, v110
	v_exp_f32_e32 v112, v112
	v_add_f32_e32 v180, v180, v111
	v_exp_f32_e32 v113, v113
	v_add_f32_e32 v180, v180, v112
	s_nop 0
	v_add_f32_e32 v180, v180, v113
	v_cvt_pk_bf16_f32 v114, v82, v83
	v_cvt_pk_bf16_f32 v115, v84, v85
	v_cvt_pk_bf16_f32 v116, v86, v87
	v_cvt_pk_bf16_f32 v117, v88, v89
	v_cvt_pk_bf16_f32 v118, v90, v91
	v_cvt_pk_bf16_f32 v119, v92, v93
	v_cvt_pk_bf16_f32 v120, v94, v95
	v_cvt_pk_bf16_f32 v121, v96, v97
	v_cvt_pk_bf16_f32 v122, v98, v99
	v_cvt_pk_bf16_f32 v123, v100, v101
	v_cvt_pk_bf16_f32 v124, v102, v103
	v_cvt_pk_bf16_f32 v125, v104, v105
	v_cvt_pk_bf16_f32 v126, v106, v107
	v_cvt_pk_bf16_f32 v127, v108, v109
	v_cvt_pk_bf16_f32 v128, v110, v111
	v_cvt_pk_bf16_f32 v129, v112, v113
	v_cmp_ngt_f32_e32 vcc, s23, v180
	s_cbranch_vccz .Lat_norescale_1
	ds_bpermute_b32 v182, v214, v180
	s_waitcnt lgkmcnt(0)
	v_add_f32_e32 v182, v180, v182
	v_min_f32_e32 v182, 0x7f61b1e6, v182
	v_log_f32_e32 v182, v182
	s_nop 0
	v_floor_f32_e32 v182, v182
	v_max_f32_e32 v182, 0, v182
	v_exp_f32_e64 v183, -v182
	v_add_f32_e32 v80, v80, v182
	v_mul_f32_e32 v81, v81, v183
	v_mul_f32_e32 v180, v180, v183
	v_xor_b32_e32 v64, 0x80000000, v80
	v_mov_b32_e32 v65, v64
	v_mov_b32_e32 v66, v64
	v_mov_b32_e32 v67, v64
	v_mov_b32_e32 v68, v64
	v_mov_b32_e32 v69, v64
	v_mov_b32_e32 v70, v64
	v_mov_b32_e32 v71, v64
	v_mov_b32_e32 v72, v64
	v_mov_b32_e32 v73, v64
	v_mov_b32_e32 v74, v64
	v_mov_b32_e32 v75, v64
	v_mov_b32_e32 v76, v64
	v_mov_b32_e32 v77, v64
	v_mov_b32_e32 v78, v64
	v_mov_b32_e32 v79, v64
	v_mul_f32_e32 v82, v82, v183
	v_mul_f32_e32 v83, v83, v183
	v_mul_f32_e32 v84, v84, v183
	v_mul_f32_e32 v85, v85, v183
	v_mul_f32_e32 v86, v86, v183
	v_mul_f32_e32 v87, v87, v183
	v_mul_f32_e32 v88, v88, v183
	v_mul_f32_e32 v89, v89, v183
	v_mul_f32_e32 v90, v90, v183
	v_mul_f32_e32 v91, v91, v183
	v_mul_f32_e32 v92, v92, v183
	v_mul_f32_e32 v93, v93, v183
	v_mul_f32_e32 v94, v94, v183
	v_mul_f32_e32 v95, v95, v183
	v_mul_f32_e32 v96, v96, v183
	v_mul_f32_e32 v97, v97, v183
	v_mul_f32_e32 v98, v98, v183
	v_mul_f32_e32 v99, v99, v183
	v_mul_f32_e32 v100, v100, v183
	v_mul_f32_e32 v101, v101, v183
	v_mul_f32_e32 v102, v102, v183
	v_mul_f32_e32 v103, v103, v183
	v_mul_f32_e32 v104, v104, v183
	v_mul_f32_e32 v105, v105, v183
	v_mul_f32_e32 v106, v106, v183
	v_mul_f32_e32 v107, v107, v183
	v_mul_f32_e32 v108, v108, v183
	v_mul_f32_e32 v109, v109, v183
	v_mul_f32_e32 v110, v110, v183
	v_mul_f32_e32 v111, v111, v183
	v_mul_f32_e32 v112, v112, v183
	v_mul_f32_e32 v113, v113, v183
	v_mul_f32_e32 v0, v0, v183
	v_mul_f32_e32 v1, v1, v183
	v_mul_f32_e32 v2, v2, v183
	v_mul_f32_e32 v3, v3, v183
	v_mul_f32_e32 v4, v4, v183
	v_mul_f32_e32 v5, v5, v183
	v_mul_f32_e32 v6, v6, v183
	v_mul_f32_e32 v7, v7, v183
	v_mul_f32_e32 v8, v8, v183
	v_mul_f32_e32 v9, v9, v183
	v_mul_f32_e32 v10, v10, v183
	v_mul_f32_e32 v11, v11, v183
	v_mul_f32_e32 v12, v12, v183
	v_mul_f32_e32 v13, v13, v183
	v_mul_f32_e32 v14, v14, v183
	v_mul_f32_e32 v15, v15, v183
	v_mul_f32_e32 v16, v16, v183
	v_mul_f32_e32 v17, v17, v183
	v_mul_f32_e32 v18, v18, v183
	v_mul_f32_e32 v19, v19, v183
	v_mul_f32_e32 v20, v20, v183
	v_mul_f32_e32 v21, v21, v183
	v_mul_f32_e32 v22, v22, v183
	v_mul_f32_e32 v23, v23, v183
	v_mul_f32_e32 v24, v24, v183
	v_mul_f32_e32 v25, v25, v183
	v_mul_f32_e32 v26, v26, v183
	v_mul_f32_e32 v27, v27, v183
	v_mul_f32_e32 v28, v28, v183
	v_mul_f32_e32 v29, v29, v183
	v_mul_f32_e32 v30, v30, v183
	v_mul_f32_e32 v31, v31, v183
	v_mul_f32_e32 v32, v32, v183
	v_mul_f32_e32 v33, v33, v183
	v_mul_f32_e32 v34, v34, v183
	v_mul_f32_e32 v35, v35, v183
	v_mul_f32_e32 v36, v36, v183
	v_mul_f32_e32 v37, v37, v183
	v_mul_f32_e32 v38, v38, v183
	v_mul_f32_e32 v39, v39, v183
	v_mul_f32_e32 v40, v40, v183
	v_mul_f32_e32 v41, v41, v183
	v_mul_f32_e32 v42, v42, v183
	v_mul_f32_e32 v43, v43, v183
	v_mul_f32_e32 v44, v44, v183
	v_mul_f32_e32 v45, v45, v183
	v_mul_f32_e32 v46, v46, v183
	v_mul_f32_e32 v47, v47, v183
	v_mul_f32_e32 v48, v48, v183
	v_mul_f32_e32 v49, v49, v183
	v_mul_f32_e32 v50, v50, v183
	v_mul_f32_e32 v51, v51, v183
	v_mul_f32_e32 v52, v52, v183
	v_mul_f32_e32 v53, v53, v183
	v_mul_f32_e32 v54, v54, v183
	v_mul_f32_e32 v55, v55, v183
	v_mul_f32_e32 v56, v56, v183
	v_mul_f32_e32 v57, v57, v183
	v_mul_f32_e32 v58, v58, v183
	v_mul_f32_e32 v59, v59, v183
	v_mul_f32_e32 v60, v60, v183
	v_mul_f32_e32 v61, v61, v183
	v_mul_f32_e32 v62, v62, v183
	v_mul_f32_e32 v63, v63, v183
	v_cvt_pk_bf16_f32 v114, v82, v83
	v_cvt_pk_bf16_f32 v115, v84, v85
	v_cvt_pk_bf16_f32 v116, v86, v87
	v_cvt_pk_bf16_f32 v117, v88, v89
	v_cvt_pk_bf16_f32 v118, v90, v91
	v_cvt_pk_bf16_f32 v119, v92, v93
	v_cvt_pk_bf16_f32 v120, v94, v95
	v_cvt_pk_bf16_f32 v121, v96, v97
	v_cvt_pk_bf16_f32 v122, v98, v99
	v_cvt_pk_bf16_f32 v123, v100, v101
	v_cvt_pk_bf16_f32 v124, v102, v103
	v_cvt_pk_bf16_f32 v125, v104, v105
	v_cvt_pk_bf16_f32 v126, v106, v107
	v_cvt_pk_bf16_f32 v127, v108, v109
	v_cvt_pk_bf16_f32 v128, v110, v111
	v_cvt_pk_bf16_f32 v129, v112, v113
.Lat_norescale_1:
	v_add_f32_e32 v81, v81, v180
	s_add_i32 s12, s12, 8192
	s_cmp_eq_u32 s12, 32768
	s_cselect_b32 s12, 0, s12
	s_cmp_lt_i32 s81, 1
	s_cbranch_scc1 .Lat_noqk1_2
	v_add_u32_e32 v188, s12, v157
	v_add_u32_e32 v189, s12, v158
	v_add_u32_e32 v222, s12, v159
	v_add_u32_e32 v223, s12, v160
	ds_read_b128 v[224:227], v188
	ds_read_b128 v[228:231], v189
	ds_read_b128 v[232:235], v222
	ds_read_b128 v[236:239], v223
	ds_read_b128 v[240:243], v188 offset:4096
	ds_read_b128 v[130:133], v189 offset:4096
	ds_read_b128 v[134:137], v222 offset:4096
	ds_read_b128 v[184:187], v223 offset:4096
	s_waitcnt lgkmcnt(7)
	v_mfma_f32_32x32x16_bf16 v[82:97], v[224:227], v[150:153], v[64:79]
	s_waitcnt lgkmcnt(6)
	v_mfma_f32_32x32x16_bf16 v[82:97], v[228:231], v[146:149], v[82:97]
	s_waitcnt lgkmcnt(5)
	v_mfma_f32_32x32x16_bf16 v[82:97], v[232:235], v[142:145], v[82:97]
	s_waitcnt lgkmcnt(4)
	v_mfma_f32_32x32x16_bf16 v[82:97], v[236:239], v[138:141], v[82:97]
	s_waitcnt lgkmcnt(3)
	v_mfma_f32_32x32x16_bf16 v[98:113], v[240:243], v[150:153], v[64:79]
	s_waitcnt lgkmcnt(2)
	v_mfma_f32_32x32x16_bf16 v[98:113], v[130:133], v[146:149], v[98:113]
	s_waitcnt lgkmcnt(1)
	v_mfma_f32_32x32x16_bf16 v[98:113], v[134:137], v[142:145], v[98:113]
	s_waitcnt lgkmcnt(0)
	v_mfma_f32_32x32x16_bf16 v[98:113], v[184:187], v[138:141], v[98:113]
.Lat_noqk1_2:
	s_mov_b32 s5, 1
	s_add_i32 s12, s12, 8192
	s_cmp_eq_u32 s12, 32768
	s_cselect_b32 s12, 0, s12
	v_add_u32_e32 v215, s84, v161
	v_add_u32_e32 v165, s84, v162
	v_add_u32_e32 v216, s84, v163
	v_add_u32_e32 v217, s84, v164
	ds_read_b64_tr_b16 v[224:225], v215 offset:0
	ds_read_b64_tr_b16 v[226:227], v215 offset:2048
	ds_read_b64_tr_b16 v[228:229], v165 offset:0
	ds_read_b64_tr_b16 v[230:231], v165 offset:2048
	ds_read_b64_tr_b16 v[232:233], v216 offset:0
	ds_read_b64_tr_b16 v[234:235], v216 offset:2048
	ds_read_b64_tr_b16 v[236:237], v217 offset:0
	ds_read_b64_tr_b16 v[238:239], v217 offset:2048
	ds_read_b64_tr_b16 v[240:241], v215 offset:4096
	ds_read_b64_tr_b16 v[242:243], v215 offset:6144
	ds_read_b64_tr_b16 v[130:131], v165 offset:4096
	ds_read_b64_tr_b16 v[132:133], v165 offset:6144
	ds_read_b64_tr_b16 v[134:135], v216 offset:4096
	ds_read_b64_tr_b16 v[136:137], v216 offset:6144
	ds_read_b64_tr_b16 v[184:185], v217 offset:4096
	ds_read_b64_tr_b16 v[186:187], v217 offset:6144
	s_waitcnt vmcnt(3) lgkmcnt(15)
	s_barrier
.Lat_loop:
	v_add_u32_e32 v188, s12, v157
	v_add_u32_e32 v189, s12, v158
	v_add_u32_e32 v222, s12, v159
	v_add_u32_e32 v223, s12, v160
	s_cmp_ge_i32 s5, s81
	s_cbranch_scc1 .Lat_rare_8
	s_waitcnt lgkmcnt(8)
	v_mfma_f32_32x32x16_bf16 v[0:15], v[224:227], v[114:117], v[0:15]
	v_exp_f32_e32 v82, v82
	v_exp_f32_e32 v83, v83
	ds_read_b64_tr_b16 v[224:225], v215 offset:8192
	ds_read_b64_tr_b16 v[226:227], v215 offset:10240
	v_mfma_f32_32x32x16_bf16 v[16:31], v[228:231], v[114:117], v[16:31]
	v_exp_f32_e32 v84, v84
	v_exp_f32_e32 v85, v85
	v_add_f32_e32 v180, v82, v83
	ds_read_b64_tr_b16 v[228:229], v165 offset:8192
	ds_read_b64_tr_b16 v[230:231], v165 offset:10240
	v_mfma_f32_32x32x16_bf16 v[32:47], v[232:235], v[114:117], v[32:47]
	v_exp_f32_e32 v86, v86
	v_exp_f32_e32 v87, v87
	v_add_f32_e32 v180, v180, v84
	v_add_f32_e32 v180, v180, v85
	ds_read_b64_tr_b16 v[232:233], v216 offset:8192
	ds_read_b64_tr_b16 v[234:235], v216 offset:10240
	v_mfma_f32_32x32x16_bf16 v[48:63], v[236:239], v[114:117], v[48:63]
	v_exp_f32_e32 v88, v88
	v_exp_f32_e32 v89, v89
	v_add_f32_e32 v180, v180, v86
	v_add_f32_e32 v180, v180, v87
	ds_read_b64_tr_b16 v[236:237], v217 offset:8192
	ds_read_b64_tr_b16 v[238:239], v217 offset:10240
	s_waitcnt lgkmcnt(8)
	v_mfma_f32_32x32x16_bf16 v[0:15], v[240:243], v[118:121], v[0:15]
	v_exp_f32_e32 v90, v90
	v_exp_f32_e32 v91, v91
	v_add_f32_e32 v180, v180, v88
	v_cvt_pk_bf16_f32 v114, v82, v83
	ds_read_b64_tr_b16 v[240:241], v215 offset:12288
	ds_read_b64_tr_b16 v[242:243], v215 offset:14336
	v_mfma_f32_32x32x16_bf16 v[16:31], v[130:133], v[118:121], v[16:31]
	v_exp_f32_e32 v92, v92
	v_exp_f32_e32 v93, v93
	v_add_f32_e32 v180, v180, v89
	v_cvt_pk_bf16_f32 v115, v84, v85
	ds_read_b64_tr_b16 v[130:131], v165 offset:12288
	ds_read_b64_tr_b16 v[132:133], v165 offset:14336
	v_mfma_f32_32x32x16_bf16 v[32:47], v[134:137], v[118:121], v[32:47]
	v_exp_f32_e32 v94, v94
	v_exp_f32_e32 v95, v95
	v_add_f32_e32 v180, v180, v90
	v_cvt_pk_bf16_f32 v116, v86, v87
	ds_read_b64_tr_b16 v[134:135], v216 offset:12288
	ds_read_b64_tr_b16 v[136:137], v216 offset:14336
	v_mfma_f32_32x32x16_bf16 v[48:63], v[184:187], v[118:121], v[48:63]
	v_exp_f32_e32 v96, v96
	v_exp_f32_e32 v97, v97
	v_add_f32_e32 v180, v180, v91
	v_cvt_pk_bf16_f32 v117, v88, v89
	ds_read_b64_tr_b16 v[184:185], v217 offset:12288
	ds_read_b64_tr_b16 v[186:187], v217 offset:14336
	s_waitcnt lgkmcnt(8)
	v_mfma_f32_32x32x16_bf16 v[0:15], v[224:227], v[122:125], v[0:15]
	v_exp_f32_e32 v98, v98
	v_exp_f32_e32 v99, v99
	v_add_f32_e32 v180, v180, v92
	v_cvt_pk_bf16_f32 v118, v90, v91
	v_mfma_f32_32x32x16_bf16 v[16:31], v[228:231], v[122:125], v[16:31]
	v_exp_f32_e32 v100, v100
	v_exp_f32_e32 v101, v101
	v_add_f32_e32 v180, v180, v93
	v_cvt_pk_bf16_f32 v119, v92, v93
	v_mfma_f32_32x32x16_bf16 v[32:47], v[232:235], v[122:125], v[32:47]
	v_exp_f32_e32 v102, v102
	v_exp_f32_e32 v103, v103
	v_add_f32_e32 v180, v180, v94
	v_cvt_pk_bf16_f32 v120, v94, v95
	v_mfma_f32_32x32x16_bf16 v[48:63], v[236:239], v[122:125], v[48:63]
	v_exp_f32_e32 v104, v104
	v_exp_f32_e32 v105, v105
	v_add_f32_e32 v180, v180, v95
	v_cvt_pk_bf16_f32 v121, v96, v97
	ds_read_b128 v[224:227], v188
	ds_read_b128 v[228:231], v189
	ds_read_b128 v[232:235], v222
	ds_read_b128 v[236:239], v223
	s_waitcnt lgkmcnt(4)
	v_mfma_f32_32x32x16_bf16 v[0:15], v[240:243], v[126:129], v[0:15]
	v_exp_f32_e32 v106, v106
	v_exp_f32_e32 v107, v107
	v_add_f32_e32 v180, v180, v96
	v_add_f32_e32 v180, v180, v97
	v_mfma_f32_32x32x16_bf16 v[16:31], v[130:133], v[126:129], v[16:31]
	v_exp_f32_e32 v108, v108
	v_exp_f32_e32 v109, v109
	v_add_f32_e32 v180, v180, v98
	v_add_f32_e32 v180, v180, v99
	v_mfma_f32_32x32x16_bf16 v[32:47], v[134:137], v[126:129], v[32:47]
	v_exp_f32_e32 v110, v110
	v_exp_f32_e32 v111, v111
	v_add_f32_e32 v180, v180, v100
	v_add_f32_e32 v180, v180, v101
	v_mfma_f32_32x32x16_bf16 v[48:63], v[184:187], v[126:129], v[48:63]
	v_exp_f32_e32 v112, v112
	v_exp_f32_e32 v113, v113
	v_add_f32_e32 v180, v180, v102
	v_add_f32_e32 v180, v180, v103
	ds_read_b128 v[240:243], v188 offset:4096
	ds_read_b128 v[130:133], v189 offset:4096
	ds_read_b128 v[134:137], v222 offset:4096
	ds_read_b128 v[184:187], v223 offset:4096
	s_waitcnt lgkmcnt(4)
	v_mfma_f32_32x32x16_bf16 v[82:97], v[224:227], v[150:153], v[64:79]
	v_add_f32_e32 v180, v180, v104
	v_add_f32_e32 v180, v180, v105
	v_add_f32_e32 v180, v180, v106
	v_cvt_pk_bf16_f32 v122, v98, v99
	v_cvt_pk_bf16_f32 v123, v100, v101
	s_add_i32 m0, s13, s68
	s_nop 0
	global_load_lds_dwordx4 v154, s[14:15]
	v_mfma_f32_32x32x16_bf16 v[82:97], v[228:231], v[146:149], v[82:97]
	v_add_f32_e32 v180, v180, v107
	v_add_f32_e32 v180, v180, v108
	v_add_f32_e32 v180, v180, v109
	v_cvt_pk_bf16_f32 v124, v102, v103
	v_cvt_pk_bf16_f32 v125, v104, v105
	s_add_i32 m0, s17, s69
	s_nop 0
	global_load_lds_dwordx4 v155, s[18:19]
	v_mfma_f32_32x32x16_bf16 v[82:97], v[232:235], v[142:145], v[82:97]
	v_add_f32_e32 v180, v180, v110
	v_add_f32_e32 v180, v180, v111
	v_cvt_pk_bf16_f32 v126, v106, v107
	v_cvt_pk_bf16_f32 v127, v108, v109
	s_add_i32 m0, m0, 0x400
	s_nop 0
	global_load_lds_dwordx4 v156, s[18:19]
	v_mfma_f32_32x32x16_bf16 v[82:97], v[236:239], v[138:141], v[82:97]
	v_add_f32_e32 v180, v180, v112
	v_add_f32_e32 v180, v180, v113
	v_cvt_pk_bf16_f32 v128, v110, v111
	v_cvt_pk_bf16_f32 v129, v112, v113
	v_cmp_ngt_f32_e32 vcc, s23, v180
	s_add_i32 s12, s12, 8192
	s_cmp_eq_u32 s12, 32768
	s_cselect_b32 s12, 0, s12
	s_add_i32 s84, s84, 16384
	s_cmp_eq_u32 s84, 114688
	s_cselect_b32 s84, 32768, s84
	s_waitcnt lgkmcnt(0)
	v_mfma_f32_32x32x16_bf16 v[98:113], v[240:243], v[150:153], v[64:79]
	v_add_u32_e32 v215, s84, v161
	v_add_u32_e32 v165, s84, v162
	v_add_u32_e32 v216, s84, v163
	v_add_u32_e32 v217, s84, v164
	ds_read_b64_tr_b16 v[224:225], v215 offset:0
	ds_read_b64_tr_b16 v[226:227], v215 offset:2048
	s_add_i32 s13, s13, 8192
	s_cmp_eq_u32 s13, 32768
	s_cselect_b32 s13, 0, s13
	v_mfma_f32_32x32x16_bf16 v[98:113], v[130:133], v[146:149], v[98:113]
	ds_read_b64_tr_b16 v[228:229], v165 offset:0
	ds_read_b64_tr_b16 v[230:231], v165 offset:2048
	ds_read_b64_tr_b16 v[232:233], v216 offset:0
	ds_read_b64_tr_b16 v[234:235], v216 offset:2048
	s_add_i32 s17, s17, 16384
	s_cmp_eq_u32 s17, 114688
	s_cselect_b32 s17, 32768, s17
	v_mfma_f32_32x32x16_bf16 v[98:113], v[134:137], v[142:145], v[98:113]
	ds_read_b64_tr_b16 v[236:237], v217 offset:0
	ds_read_b64_tr_b16 v[238:239], v217 offset:2048
	v_mfma_f32_32x32x16_bf16 v[98:113], v[184:187], v[138:141], v[98:113]
	s_add_i32 s85, s85, 1
	s_cmp_eq_u32 s85, s6
	s_cselect_b32 s8, s10, 0x40000
	s_cselect_b32 s16, s11, 0
	s_cselect_b32 s9, 0x80, 0
	s_add_u32 s18, s18, s8
	s_addc_u32 s19, s19, s16
	s_add_u32 s14, s14, s8
	s_addc_u32 s15, s15, s16
	s_add_u32 s14, s14, s9
	s_addc_u32 s15, s15, 0
	ds_read_b64_tr_b16 v[240:241], v215 offset:4096
	ds_read_b64_tr_b16 v[242:243], v215 offset:6144
	ds_read_b64_tr_b16 v[130:131], v165 offset:4096
	ds_read_b64_tr_b16 v[132:133], v165 offset:6144
	ds_read_b64_tr_b16 v[134:135], v216 offset:4096
	ds_read_b64_tr_b16 v[136:137], v216 offset:6144
	ds_read_b64_tr_b16 v[184:185], v217 offset:4096
	ds_read_b64_tr_b16 v[186:187], v217 offset:6144
	s_cbranch_vccz .Lat_norescale_9
	ds_bpermute_b32 v182, v214, v180
	s_waitcnt lgkmcnt(0)
	v_add_f32_e32 v182, v180, v182
	v_min_f32_e32 v182, 0x7f61b1e6, v182
	v_log_f32_e32 v182, v182
	s_nop 0
	v_floor_f32_e32 v182, v182
	v_max_f32_e32 v182, 0, v182
	v_exp_f32_e64 v183, -v182
	v_add_f32_e32 v80, v80, v182
	v_mul_f32_e32 v81, v81, v183
	v_mul_f32_e32 v180, v180, v183
	v_xor_b32_e32 v64, 0x80000000, v80
	v_mov_b32_e32 v65, v64
	v_mov_b32_e32 v66, v64
	v_mov_b32_e32 v67, v64
	v_mov_b32_e32 v68, v64
	v_mov_b32_e32 v69, v64
	v_mov_b32_e32 v70, v64
	v_mov_b32_e32 v71, v64
	v_mov_b32_e32 v72, v64
	v_mov_b32_e32 v73, v64
	v_mov_b32_e32 v74, v64
	v_mov_b32_e32 v75, v64
	v_mov_b32_e32 v76, v64
	v_mov_b32_e32 v77, v64
	v_mov_b32_e32 v78, v64
	v_mov_b32_e32 v79, v64
	v_sub_f32_e32 v82, v82, v182
	v_sub_f32_e32 v83, v83, v182
	v_sub_f32_e32 v84, v84, v182
	v_sub_f32_e32 v85, v85, v182
	v_sub_f32_e32 v86, v86, v182
	v_sub_f32_e32 v87, v87, v182
	v_sub_f32_e32 v88, v88, v182
	v_sub_f32_e32 v89, v89, v182
	v_sub_f32_e32 v90, v90, v182
	v_sub_f32_e32 v91, v91, v182
	v_sub_f32_e32 v92, v92, v182
	v_sub_f32_e32 v93, v93, v182
	v_sub_f32_e32 v94, v94, v182
	v_sub_f32_e32 v95, v95, v182
	v_sub_f32_e32 v96, v96, v182
	v_sub_f32_e32 v97, v97, v182
	v_sub_f32_e32 v98, v98, v182
	v_sub_f32_e32 v99, v99, v182
	v_sub_f32_e32 v100, v100, v182
	v_sub_f32_e32 v101, v101, v182
	v_sub_f32_e32 v102, v102, v182
	v_sub_f32_e32 v103, v103, v182
	v_sub_f32_e32 v104, v104, v182
	v_sub_f32_e32 v105, v105, v182
	v_sub_f32_e32 v106, v106, v182
	v_sub_f32_e32 v107, v107, v182
	v_sub_f32_e32 v108, v108, v182
	v_sub_f32_e32 v109, v109, v182
	v_sub_f32_e32 v110, v110, v182
	v_sub_f32_e32 v111, v111, v182
	v_sub_f32_e32 v112, v112, v182
	v_sub_f32_e32 v113, v113, v182
	v_mul_f32_e32 v0, v0, v183
	v_mul_f32_e32 v1, v1, v183
	v_mul_f32_e32 v2, v2, v183
	v_mul_f32_e32 v3, v3, v183
	v_mul_f32_e32 v4, v4, v183
	v_mul_f32_e32 v5, v5, v183
	v_mul_f32_e32 v6, v6, v183
	v_mul_f32_e32 v7, v7, v183
	v_mul_f32_e32 v8, v8, v183
	v_mul_f32_e32 v9, v9, v183
	v_mul_f32_e32 v10, v10, v183
	v_mul_f32_e32 v11, v11, v183
	v_mul_f32_e32 v12, v12, v183
	v_mul_f32_e32 v13, v13, v183
	v_mul_f32_e32 v14, v14, v183
	v_mul_f32_e32 v15, v15, v183
	v_mul_f32_e32 v16, v16, v183
	v_mul_f32_e32 v17, v17, v183
	v_mul_f32_e32 v18, v18, v183
	v_mul_f32_e32 v19, v19, v183
	v_mul_f32_e32 v20, v20, v183
	v_mul_f32_e32 v21, v21, v183
	v_mul_f32_e32 v22, v22, v183
	v_mul_f32_e32 v23, v23, v183
	v_mul_f32_e32 v24, v24, v183
	v_mul_f32_e32 v25, v25, v183
	v_mul_f32_e32 v26, v26, v183
	v_mul_f32_e32 v27, v27, v183
	v_mul_f32_e32 v28, v28, v183
	v_mul_f32_e32 v29, v29, v183
	v_mul_f32_e32 v30, v30, v183
	v_mul_f32_e32 v31, v31, v183
	v_mul_f32_e32 v32, v32, v183
	v_mul_f32_e32 v33, v33, v183
	v_mul_f32_e32 v34, v34, v183
	v_mul_f32_e32 v35, v35, v183
	v_mul_f32_e32 v36, v36, v183
	v_mul_f32_e32 v37, v37, v183
	v_mul_f32_e32 v38, v38, v183
	v_mul_f32_e32 v39, v39, v183
	v_mul_f32_e32 v40, v40, v183
	v_mul_f32_e32 v41, v41, v183
	v_mul_f32_e32 v42, v42, v183
	v_mul_f32_e32 v43, v43, v183
	v_mul_f32_e32 v44, v44, v183
	v_mul_f32_e32 v45, v45, v183
	v_mul_f32_e32 v46, v46, v183
	v_mul_f32_e32 v47, v47, v183
	v_mul_f32_e32 v48, v48, v183
	v_mul_f32_e32 v49, v49, v183
	v_mul_f32_e32 v50, v50, v183
	v_mul_f32_e32 v51, v51, v183
	v_mul_f32_e32 v52, v52, v183
	v_mul_f32_e32 v53, v53, v183
	v_mul_f32_e32 v54, v54, v183
	v_mul_f32_e32 v55, v55, v183
	v_mul_f32_e32 v56, v56, v183
	v_mul_f32_e32 v57, v57, v183
	v_mul_f32_e32 v58, v58, v183
	v_mul_f32_e32 v59, v59, v183
	v_mul_f32_e32 v60, v60, v183
	v_mul_f32_e32 v61, v61, v183
	v_mul_f32_e32 v62, v62, v183
	v_mul_f32_e32 v63, v63, v183
	v_lshlrev_b32_e32 v181, 16, v114
	v_and_b32_e32 v114, 0xffff0000, v114
	v_mul_f32_e32 v181, v181, v183
	v_mul_f32_e32 v114, v114, v183
	v_cvt_pk_bf16_f32 v114, v181, v114
	v_lshlrev_b32_e32 v181, 16, v115
	v_and_b32_e32 v115, 0xffff0000, v115
	v_mul_f32_e32 v181, v181, v183
	v_mul_f32_e32 v115, v115, v183
	v_cvt_pk_bf16_f32 v115, v181, v115
	v_lshlrev_b32_e32 v181, 16, v116
	v_and_b32_e32 v116, 0xffff0000, v116
	v_mul_f32_e32 v181, v181, v183
	v_mul_f32_e32 v116, v116, v183
	v_cvt_pk_bf16_f32 v116, v181, v116
	v_lshlrev_b32_e32 v181, 16, v117
	v_and_b32_e32 v117, 0xffff0000, v117
	v_mul_f32_e32 v181, v181, v183
	v_mul_f32_e32 v117, v117, v183
	v_cvt_pk_bf16_f32 v117, v181, v117
	v_lshlrev_b32_e32 v181, 16, v118
	v_and_b32_e32 v118, 0xffff0000, v118
	v_mul_f32_e32 v181, v181, v183
	v_mul_f32_e32 v118, v118, v183
	v_cvt_pk_bf16_f32 v118, v181, v118
	v_lshlrev_b32_e32 v181, 16, v119
	v_and_b32_e32 v119, 0xffff0000, v119
	v_mul_f32_e32 v181, v181, v183
	v_mul_f32_e32 v119, v119, v183
	v_cvt_pk_bf16_f32 v119, v181, v119
	v_lshlrev_b32_e32 v181, 16, v120
	v_and_b32_e32 v120, 0xffff0000, v120
	v_mul_f32_e32 v181, v181, v183
	v_mul_f32_e32 v120, v120, v183
	v_cvt_pk_bf16_f32 v120, v181, v120
	v_lshlrev_b32_e32 v181, 16, v121
	v_and_b32_e32 v121, 0xffff0000, v121
	v_mul_f32_e32 v181, v181, v183
	v_mul_f32_e32 v121, v121, v183
	v_cvt_pk_bf16_f32 v121, v181, v121
	v_lshlrev_b32_e32 v181, 16, v122
	v_and_b32_e32 v122, 0xffff0000, v122
	v_mul_f32_e32 v181, v181, v183
	v_mul_f32_e32 v122, v122, v183
	v_cvt_pk_bf16_f32 v122, v181, v122
	v_lshlrev_b32_e32 v181, 16, v123
	v_and_b32_e32 v123, 0xffff0000, v123
	v_mul_f32_e32 v181, v181, v183
	v_mul_f32_e32 v123, v123, v183
	v_cvt_pk_bf16_f32 v123, v181, v123
	v_lshlrev_b32_e32 v181, 16, v124
	v_and_b32_e32 v124, 0xffff0000, v124
	v_mul_f32_e32 v181, v181, v183
	v_mul_f32_e32 v124, v124, v183
	v_cvt_pk_bf16_f32 v124, v181, v124
	v_lshlrev_b32_e32 v181, 16, v125
	v_and_b32_e32 v125, 0xffff0000, v125
	v_mul_f32_e32 v181, v181, v183
	v_mul_f32_e32 v125, v125, v183
	v_cvt_pk_bf16_f32 v125, v181, v125
	v_lshlrev_b32_e32 v181, 16, v126
	v_and_b32_e32 v126, 0xffff0000, v126
	v_mul_f32_e32 v181, v181, v183
	v_mul_f32_e32 v126, v126, v183
	v_cvt_pk_bf16_f32 v126, v181, v126
	v_lshlrev_b32_e32 v181, 16, v127
	v_and_b32_e32 v127, 0xffff0000, v127
	v_mul_f32_e32 v181, v181, v183
	v_mul_f32_e32 v127, v127, v183
	v_cvt_pk_bf16_f32 v127, v181, v127
	v_lshlrev_b32_e32 v181, 16, v128
	v_and_b32_e32 v128, 0xffff0000, v128
	v_mul_f32_e32 v181, v181, v183
	v_mul_f32_e32 v128, v128, v183
	v_cvt_pk_bf16_f32 v128, v181, v128
	v_lshlrev_b32_e32 v181, 16, v129
	v_and_b32_e32 v129, 0xffff0000, v129
	v_mul_f32_e32 v181, v181, v183
	v_mul_f32_e32 v129, v129, v183
	v_cvt_pk_bf16_f32 v129, v181, v129

.Lat_noqk_3:
	s_add_i32 m0, s13, s68
	s_nop 0
	global_load_lds_dwordx4 v154, s[14:15]
	s_add_i32 m0, s17, s69
	s_nop 0
	global_load_lds_dwordx4 v155, s[18:19]
	s_add_i32 m0, m0, 0x400
	s_nop 0
	global_load_lds_dwordx4 v156, s[18:19]
	s_add_i32 s13, s13, 8192
	s_cmp_eq_u32 s13, 32768
	s_cselect_b32 s13, 0, s13
	s_add_i32 s17, s17, 16384
	s_cmp_eq_u32 s17, 114688
	s_cselect_b32 s17, 32768, s17
	s_add_i32 s85, s85, 1
	s_cmp_eq_u32 s85, s6
	s_cselect_b32 s8, s10, 0x40000
	s_cselect_b32 s16, s11, 0
	s_cselect_b32 s9, 0x80, 0
	s_add_u32 s18, s18, s8
	s_addc_u32 s19, s19, s16
	s_add_u32 s14, s14, s8
	s_addc_u32 s15, s15, s16
	s_add_u32 s14, s14, s9
	s_addc_u32 s15, s15, 0
	s_add_i32 s5, s5, 1
	s_add_i32 s12, s12, 8192
	s_cmp_eq_u32 s12, 32768
	s_cselect_b32 s12, 0, s12
	s_add_i32 s84, s84, 16384
	s_cmp_eq_u32 s84, 114688
	s_cselect_b32 s84, 32768, s84
	s_add_i32 s16, s81, 1
	s_cmp_gt_i32 s5, s16
	s_cbranch_scc1 .Lat_novpre_5
	v_add_u32_e32 v215, s84, v161
	v_add_u32_e32 v165, s84, v162
	v_add_u32_e32 v216, s84, v163
	v_add_u32_e32 v217, s84, v164
	ds_read_b64_tr_b16 v[224:225], v215 offset:0
	ds_read_b64_tr_b16 v[226:227], v215 offset:2048
	ds_read_b64_tr_b16 v[228:229], v165 offset:0
	ds_read_b64_tr_b16 v[230:231], v165 offset:2048
	ds_read_b64_tr_b16 v[232:233], v216 offset:0
	ds_read_b64_tr_b16 v[234:235], v216 offset:2048
	ds_read_b64_tr_b16 v[236:237], v217 offset:0
	ds_read_b64_tr_b16 v[238:239], v217 offset:2048
	ds_read_b64_tr_b16 v[240:241], v215 offset:4096
	ds_read_b64_tr_b16 v[242:243], v215 offset:6144
	ds_read_b64_tr_b16 v[130:131], v165 offset:4096
	ds_read_b64_tr_b16 v[132:133], v165 offset:6144
	ds_read_b64_tr_b16 v[134:135], v216 offset:4096
	ds_read_b64_tr_b16 v[136:137], v216 offset:6144
	ds_read_b64_tr_b16 v[184:185], v217 offset:4096
	ds_read_b64_tr_b16 v[186:187], v217 offset:6144
	s_waitcnt vmcnt(3) lgkmcnt(15)
	s_branch .Lat_bottom_4

.Lat_loopexit:
	s_cmp_lg_u32 s7, 0
	s_cbranch_scc1 .Lat_noqpre_12
	s_mov_b64 s[8:9], 0x80
	v_lshl_add_u64 v[182:183], v[166:167], 0, s[8:9]
	global_load_dwordx4 v[150:153], v[182:183], off
	global_load_dwordx4 v[146:149], v[182:183], off offset:32
	global_load_dwordx4 v[142:145], v[182:183], off offset:64
	global_load_dwordx4 v[138:141], v[182:183], off offset:96

.Lat_nolast_11:
	s_cmp_lg_u32 s7, 0
	s_cbranch_scc1 .Lat_drainw_13
	s_waitcnt vmcnt(4) lgkmcnt(0)
	s_branch .Lat_drainj_14

.Lat_drainj_14:
	s_barrier
	ds_bpermute_b32 v182, v214, v81
	s_waitcnt lgkmcnt(0)
	v_add_f32_e32 v64, v81, v182
	v_div_scale_f32 v65, s[36:37], v64, v64, 1.0
	v_rcp_f32_e32 v66, v65
	v_div_scale_f32 v67, vcc, 1.0, v64, 1.0
	v_fma_f32 v68, -v65, v66, 1.0
	v_fmac_f32_e32 v66, v68, v66
	v_mul_f32_e32 v68, v67, v66
	v_fma_f32 v69, -v65, v68, v67
	v_fmac_f32_e32 v68, v69, v66
	v_fma_f32 v65, -v65, v68, v67
	v_div_fmas_f32 v65, v65, v66, v68
	v_div_fixup_f32 v72, v65, v64, 1.0
	v_mul_f32_e32 v0, v0, v72
	v_mul_f32_e32 v1, v1, v72
	v_mul_f32_e32 v2, v2, v72
	v_mul_f32_e32 v3, v3, v72
	v_mul_f32_e32 v4, v4, v72
	v_mul_f32_e32 v5, v5, v72
	v_mul_f32_e32 v6, v6, v72
	v_mul_f32_e32 v7, v7, v72
	v_mul_f32_e32 v8, v8, v72
	v_mul_f32_e32 v9, v9, v72
	v_mul_f32_e32 v10, v10, v72
	v_mul_f32_e32 v11, v11, v72
	v_mul_f32_e32 v12, v12, v72
	v_mul_f32_e32 v13, v13, v72
	v_mul_f32_e32 v14, v14, v72
	v_mul_f32_e32 v15, v15, v72
	v_mul_f32_e32 v16, v16, v72
	v_mul_f32_e32 v17, v17, v72
	v_mul_f32_e32 v18, v18, v72
	v_mul_f32_e32 v19, v19, v72
	v_mul_f32_e32 v20, v20, v72
	v_mul_f32_e32 v21, v21, v72
	v_mul_f32_e32 v22, v22, v72
	v_mul_f32_e32 v23, v23, v72
	v_mul_f32_e32 v24, v24, v72
	v_mul_f32_e32 v25, v25, v72
	v_mul_f32_e32 v26, v26, v72
	v_mul_f32_e32 v27, v27, v72
	v_mul_f32_e32 v28, v28, v72
	v_mul_f32_e32 v29, v29, v72
	v_mul_f32_e32 v30, v30, v72
	v_mul_f32_e32 v31, v31, v72
	v_mul_f32_e32 v32, v32, v72
	v_mul_f32_e32 v33, v33, v72
	v_mul_f32_e32 v34, v34, v72
	v_mul_f32_e32 v35, v35, v72
	v_mul_f32_e32 v36, v36, v72
	v_mul_f32_e32 v37, v37, v72
	v_mul_f32_e32 v38, v38, v72
	v_mul_f32_e32 v39, v39, v72
	v_mul_f32_e32 v40, v40, v72
	v_mul_f32_e32 v41, v41, v72
	v_mul_f32_e32 v42, v42, v72
	v_mul_f32_e32 v43, v43, v72
	v_mul_f32_e32 v44, v44, v72
	v_mul_f32_e32 v45, v45, v72
	v_mul_f32_e32 v46, v46, v72
	v_mul_f32_e32 v47, v47, v72
	v_mul_f32_e32 v48, v48, v72
	v_mul_f32_e32 v49, v49, v72
	v_mul_f32_e32 v50, v50, v72
	v_mul_f32_e32 v51, v51, v72
	v_mul_f32_e32 v52, v52, v72
	v_mul_f32_e32 v53, v53, v72
	v_mul_f32_e32 v54, v54, v72
	v_mul_f32_e32 v55, v55, v72
	v_mul_f32_e32 v56, v56, v72
	v_mul_f32_e32 v57, v57, v72
	v_mul_f32_e32 v58, v58, v72
	v_mul_f32_e32 v59, v59, v72
	v_mul_f32_e32 v60, v60, v72
	v_mul_f32_e32 v61, v61, v72
	v_mul_f32_e32 v62, v62, v72
	v_mul_f32_e32 v63, v63, v72
	s_cmp_lg_u32 s7, 0
	s_cbranch_scc1 .Lat_combine
	global_store_dwordx4 v[170:171], v[0:3], off
	global_store_dwordx4 v[170:171], v[4:7], off offset:16
	global_store_dwordx4 v[170:171], v[8:11], off offset:32
	global_store_dwordx4 v[170:171], v[12:15], off offset:48
	global_store_dwordx4 v[170:171], v[16:19], off offset:64
	global_store_dwordx4 v[170:171], v[20:23], off offset:80
	global_store_dwordx4 v[170:171], v[24:27], off offset:96
	global_store_dwordx4 v[170:171], v[28:31], off offset:112
	global_store_dwordx4 v[170:171], v[32:35], off offset:128
	global_store_dwordx4 v[170:171], v[36:39], off offset:144
	global_store_dwordx4 v[170:171], v[40:43], off offset:160
	global_store_dwordx4 v[170:171], v[44:47], off offset:176
	global_store_dwordx4 v[170:171], v[48:51], off offset:192
	global_store_dwordx4 v[170:171], v[52:55], off offset:208
	global_store_dwordx4 v[170:171], v[56:59], off offset:224
	global_store_dwordx4 v[170:171], v[60:63], off offset:240
	s_mov_b32 s7, 1
	s_branch .Lat_stream1
